# P8 conv epilogue: broadcast-pair moves folded into v_pk_mul op_sel_hi, one 4-move+pk_mul group rewritten as two scalar multiplies (17 VALU fewer per tile, same arithmetic)
# baseline (speedup 1.0000x reference)
.LBB0_768:
	v_pk_mul_f32 v[210:211], v[148:149], v[208:209] op_sel_hi:[1,0]
	s_waitcnt lgkmcnt(0)
	v_mov_b32_dpp v172, v164 row_shr:1 row_mask:0xf bank_mask:0xf
	v_mov_b32_dpp v173, v165 row_shr:1 row_mask:0xf bank_mask:0xf
	v_mov_b32_dpp v148, v210 row_ror:15 row_mask:0xf bank_mask:0xf
	v_mov_b32_dpp v149, v211 row_ror:15 row_mask:0xf bank_mask:0xf
	s_waitcnt vmcnt(0)
	v_pk_fma_f32 v[172:173], v[80:81], v[172:173], v[84:85]
	v_pk_mul_f32 v[206:207], v[150:151], v[208:209] op_sel_hi:[1,0]
	v_mov_b32_dpp v174, v166 row_shr:1 row_mask:0xf bank_mask:0xf
	v_mov_b32_dpp v175, v167 row_shr:1 row_mask:0xf bank_mask:0xf
	v_mov_b32_dpp v148, v164 row_shl:1 row_mask:0xf bank_mask:0xf
	v_mov_b32_dpp v149, v165 row_shl:1 row_mask:0xf bank_mask:0xf
	v_pk_fma_f32 v[172:173], v[164:165], v[76:77], v[172:173]
	v_mov_b32_dpp v150, v206 row_ror:15 row_mask:0xf bank_mask:0xf
	v_mov_b32_dpp v151, v207 row_ror:15 row_mask:0xf bank_mask:0xf
	v_pk_fma_f32 v[174:175], v[82:83], v[174:175], v[86:87]
	v_pk_fma_f32 v[148:149], v[72:73], v[148:149], v[172:173]
	v_mov_b32_dpp v150, v166 row_shl:1 row_mask:0xf bank_mask:0xf
	v_mov_b32_dpp v151, v167 row_shl:1 row_mask:0xf bank_mask:0xf
	v_pk_fma_f32 v[174:175], v[166:167], v[78:79], v[174:175]
	v_pk_mul_f32 v[172:173], v[148:149], v[148:149]
	v_pk_fma_f32 v[150:151], v[74:75], v[150:151], v[174:175]
	v_pk_mul_f32 v[172:173], v[148:149], v[172:173]
	v_pk_mul_f32 v[174:175], v[150:151], v[150:151]
	v_pk_fma_f32 v[172:173], v[172:173], s[70:71], v[148:149] op_sel_hi:[1,0,1]
	v_pk_mul_f32 v[174:175], v[150:151], v[174:175]
	v_pk_mul_f32 v[172:173], v[172:173], s[72:73] op_sel_hi:[1,0]
	v_pk_fma_f32 v[174:175], v[174:175], s[70:71], v[150:151] op_sel_hi:[1,0,1]
	v_min_f32_e32 v172, 0x41e6d4ca, v172
	v_pk_mul_f32 v[174:175], v[174:175], s[72:73] op_sel_hi:[1,0]
	v_exp_f32_e32 v233, v172
	v_min_f32_e32 v172, 0x41e6d4ca, v173
	v_exp_f32_e32 v232, v172
	v_min_f32_e32 v172, 0x41e6d4ca, v174
	v_exp_f32_e32 v173, v172
	v_min_f32_e32 v172, 0x41e6d4ca, v175
	v_exp_f32_e32 v172, v172
	v_pk_mul_f32 v[146:147], v[146:147], v[212:213] op_sel_hi:[1,0]
	v_pk_mul_f32 v[144:145], v[144:145], v[212:213]
	v_pk_mul_f32 v[138:139], v[138:139], v[212:213] op_sel_hi:[1,0]
	v_pk_mul_f32 v[136:137], v[136:137], v[212:213]
	v_pk_add_f32 v[212:213], v[232:233], 1.0 op_sel_hi:[1,0]
	v_pk_add_f32 v[230:231], v[172:173], 1.0 op_sel_hi:[1,0]
	v_mul_f32_e32 v232, v213, v212
	v_mul_f32_e32 v233, v231, v230
	v_pk_mul_f32 v[174:175], v[140:141], v[208:209] op_sel_hi:[1,0]
	v_mul_f32_e32 v172, v232, v233
	v_rcp_f32_e32 v199, v172
	v_mov_b32_dpp v168, v160 row_shr:1 row_mask:0xf bank_mask:0xf
	v_mov_b32_dpp v169, v161 row_shr:1 row_mask:0xf bank_mask:0xf
	v_pk_fma_f32 v[168:169], v[64:65], v[168:169], v[68:69]
	v_mul_f32_e32 v140, v232, v199
	v_pk_mul_f32 v[230:231], v[230:231], v[140:141] op_sel_hi:[1,0]
	v_pk_mul_f32 v[172:173], v[142:143], v[208:209] op_sel_hi:[1,0]
	v_mov_b32_dpp v140, v174 row_ror:15 row_mask:0xf bank_mask:0xf
	v_mov_b32_dpp v141, v175 row_ror:15 row_mask:0xf bank_mask:0xf
	v_mov_b32_dpp v170, v162 row_shr:1 row_mask:0xf bank_mask:0xf
	v_mov_b32_dpp v171, v163 row_shr:1 row_mask:0xf bank_mask:0xf
	v_mov_b32_dpp v140, v160 row_shl:1 row_mask:0xf bank_mask:0xf
	v_mov_b32_dpp v141, v161 row_shl:1 row_mask:0xf bank_mask:0xf
	v_pk_fma_f32 v[168:169], v[160:161], v[60:61], v[168:169]
	v_mov_b32_dpp v142, v172 row_ror:15 row_mask:0xf bank_mask:0xf
	v_mov_b32_dpp v143, v173 row_ror:15 row_mask:0xf bank_mask:0xf
	v_pk_fma_f32 v[170:171], v[66:67], v[170:171], v[70:71]
	v_pk_fma_f32 v[140:141], v[56:57], v[140:141], v[168:169]
	v_mov_b32_dpp v142, v162 row_shl:1 row_mask:0xf bank_mask:0xf
	v_mov_b32_dpp v143, v163 row_shl:1 row_mask:0xf bank_mask:0xf
	v_pk_fma_f32 v[170:171], v[162:163], v[62:63], v[170:171]
	v_pk_mul_f32 v[168:169], v[140:141], v[140:141]
	v_pk_fma_f32 v[142:143], v[58:59], v[142:143], v[170:171]
	v_pk_mul_f32 v[168:169], v[140:141], v[168:169]
	v_pk_mul_f32 v[170:171], v[142:143], v[142:143]
	v_pk_fma_f32 v[168:169], v[168:169], s[70:71], v[140:141] op_sel_hi:[1,0,1]
	v_pk_mul_f32 v[170:171], v[142:143], v[170:171]
	v_pk_mul_f32 v[168:169], v[168:169], s[72:73] op_sel_hi:[1,0]
	v_pk_fma_f32 v[170:171], v[170:171], s[70:71], v[142:143] op_sel_hi:[1,0,1]
	v_min_f32_e32 v168, 0x41e6d4ca, v168
	v_mul_f32_e32 v234, v233, v199
	v_pk_mul_f32 v[170:171], v[170:171], s[72:73] op_sel_hi:[1,0]
	v_exp_f32_e32 v233, v168
	v_min_f32_e32 v168, 0x41e6d4ca, v169
	v_exp_f32_e32 v232, v168
	v_min_f32_e32 v168, 0x41e6d4ca, v170
	v_exp_f32_e32 v169, v168
	v_min_f32_e32 v168, 0x41e6d4ca, v171
	v_exp_f32_e32 v168, v168
	v_pk_mul_f32 v[170:171], v[212:213], v[234:235] op_sel_hi:[1,0]
	v_pk_add_f32 v[212:213], v[232:233], 1.0 op_sel_hi:[1,0]
	v_pk_mul_f32 v[170:171], v[148:149], v[170:171]
	v_pk_add_f32 v[168:169], v[168:169], 1.0 op_sel_hi:[1,0]
	v_mul_f32_e32 v232, v213, v212
	s_nop 0
	v_mul_f32_e32 v233, v169, v168
	v_pk_mul_f32 v[170:171], v[144:145], v[170:171]
	v_mul_f32_e32 v199, v232, v233
	v_rcp_f32_e32 v199, v199
	v_add_u32_e32 v197, s11, v217
	v_pk_mul_f32 v[230:231], v[150:151], v[230:231]
	s_lshl_b32 s12, s10, 1
	v_mul_f32_e32 v234, v233, v199
	v_mul_f32_e32 v232, v232, v199
	v_pk_mul_f32 v[212:213], v[212:213], v[234:235] op_sel_hi:[1,0]
	v_pk_mul_f32 v[168:169], v[168:169], v[232:233] op_sel_hi:[1,0]
	v_pk_mul_f32 v[212:213], v[140:141], v[212:213]
	v_pk_mul_f32 v[168:169], v[142:143], v[168:169]
	v_pk_mul_f32 v[212:213], v[136:137], v[212:213]
	v_pk_mul_f32 v[232:233], v[138:139], v[168:169]
	v_cvt_pk_bf16_f32 v168, v170, v171
	v_cvt_pk_bf16_f32 v170, v212, v213
	v_mov_b64_e32 v[212:213], s[86:87]
	s_mul_i32 s15, s10, 0x10800
	v_pk_mul_f32 v[230:231], v[146:147], v[230:231]
	v_mad_i64_i32 v[212:213], s[10:11], v197, s90, v[212:213]
	s_mul_hi_i32 s16, s12, 0x8400
	v_cvt_pk_bf16_f32 v169, v230, v231
	v_cvt_pk_bf16_f32 v171, v232, v233
	v_lshl_add_u64 v[212:213], v[192:193], 1, v[212:213]
	global_store_dwordx4 v[212:213], v[168:171], off
	s_and_saveexec_b64 s[10:11], s[40:41]
	s_cbranch_execz .LBB0_770
	s_add_u32 s24, s4, s15
	s_addc_u32 s25, s5, s16
	v_lshl_add_u64 v[168:169], v[192:193], 2, s[24:25]
	global_store_dwordx4 v[168:169], v[148:151], off
	s_nop 1
	v_add_co_u32_e32 v148, vcc, 0x2000, v168
	s_nop 1
	v_addc_co_u32_e32 v149, vcc, 0, v169, vcc
	v_add_co_u32_e32 v150, vcc, 0x5000, v168
	global_store_dwordx4 v[148:149], v[164:167], off offset:3072
	s_nop 0
	v_addc_co_u32_e32 v151, vcc, 0, v169, vcc
	global_store_dwordx4 v[150:151], v[144:147], off offset:2048
	global_store_dwordx4 v[168:169], v[140:143], off offset:16
	global_store_dwordx4 v[148:149], v[160:163], off offset:3088
	global_store_dwordx4 v[150:151], v[136:139], off offset:2064
.LBB0_770:
	s_or_b64 exec, exec, s[10:11]
	v_pk_mul_f32 v[140:141], v[116:117], v[208:209] op_sel_hi:[1,0]
	v_pk_mul_f32 v[116:117], v[120:121], v[202:203] op_sel_hi:[1,0]
	v_pk_mul_f32 v[102:103], v[102:103], v[204:205] op_sel_hi:[1,0]
	v_pk_mul_f32 v[98:99], v[98:99], v[204:205] op_sel_hi:[1,0]
	v_mov_b32_dpp v120, v164 row_ror:1 row_mask:0xf bank_mask:0xf
	v_mov_b32_dpp v121, v165 row_ror:1 row_mask:0xf bank_mask:0xf
	v_pk_mul_f32 v[138:139], v[118:119], v[208:209] op_sel_hi:[1,0]
	v_pk_mul_f32 v[136:137], v[114:115], v[208:209] op_sel_hi:[1,0]
	v_pk_mul_f32 v[118:119], v[126:127], v[202:203] op_sel_hi:[1,0]
	v_pk_mul_f32 v[124:125], v[124:125], v[202:203] op_sel_hi:[1,0]
	v_pk_mul_f32 v[114:115], v[122:123], v[202:203] op_sel_hi:[1,0]
	v_mov_b32_dpp v120, v210 row_shr:1 row_mask:0xf bank_mask:0xf
	v_mov_b32_dpp v121, v211 row_shr:1 row_mask:0xf bank_mask:0xf
	v_mov_b32_dpp v122, v166 row_ror:1 row_mask:0xf bank_mask:0xf
	v_mov_b32_dpp v123, v167 row_ror:1 row_mask:0xf bank_mask:0xf
	v_mov_b32_dpp v126, v124 row_ror:15 row_mask:0xf bank_mask:0xf
	v_mov_b32_dpp v127, v125 row_ror:15 row_mask:0xf bank_mask:0xf
	v_pk_fma_f32 v[120:121], v[80:81], v[120:121], v[84:85]
	v_mov_b32_dpp v122, v206 row_shr:1 row_mask:0xf bank_mask:0xf
	v_mov_b32_dpp v123, v207 row_shr:1 row_mask:0xf bank_mask:0xf
	v_mov_b32_dpp v126, v210 row_shl:1 row_mask:0xf bank_mask:0xf
	v_mov_b32_dpp v127, v211 row_shl:1 row_mask:0xf bank_mask:0xf
	v_pk_fma_f32 v[120:121], v[210:211], v[76:77], v[120:121]
	v_mov_b32_dpp v142, v118 row_ror:15 row_mask:0xf bank_mask:0xf
	v_mov_b32_dpp v143, v119 row_ror:15 row_mask:0xf bank_mask:0xf
	v_pk_fma_f32 v[122:123], v[82:83], v[122:123], v[86:87]
	v_pk_fma_f32 v[120:121], v[72:73], v[126:127], v[120:121]
	v_mov_b32_dpp v142, v206 row_shl:1 row_mask:0xf bank_mask:0xf
	v_mov_b32_dpp v143, v207 row_shl:1 row_mask:0xf bank_mask:0xf
	v_pk_fma_f32 v[122:123], v[206:207], v[78:79], v[122:123]
	v_pk_mul_f32 v[126:127], v[120:121], v[120:121]
	v_pk_fma_f32 v[122:123], v[74:75], v[142:143], v[122:123]
	v_pk_mul_f32 v[126:127], v[120:121], v[126:127]
	v_pk_mul_f32 v[142:143], v[122:123], v[122:123]
	v_pk_fma_f32 v[126:127], v[126:127], s[70:71], v[120:121] op_sel_hi:[1,0,1]
	v_pk_mul_f32 v[142:143], v[122:123], v[142:143]
	v_pk_mul_f32 v[126:127], v[126:127], s[72:73] op_sel_hi:[1,0]
	v_pk_fma_f32 v[142:143], v[142:143], s[70:71], v[122:123] op_sel_hi:[1,0,1]
	v_min_f32_e32 v126, 0x41e6d4ca, v126
	v_pk_mul_f32 v[142:143], v[142:143], s[72:73] op_sel_hi:[1,0]
	v_exp_f32_e32 v145, v126
	v_min_f32_e32 v126, 0x41e6d4ca, v127
	v_exp_f32_e32 v144, v126
	v_min_f32_e32 v126, 0x41e6d4ca, v142
	v_exp_f32_e32 v127, v126
	v_min_f32_e32 v126, 0x41e6d4ca, v143
	v_exp_f32_e32 v126, v126
	v_pk_add_f32 v[142:143], v[144:145], 1.0 op_sel_hi:[1,0]
	v_pk_mul_f32 v[112:113], v[112:113], v[208:209] op_sel_hi:[1,0]
	v_pk_add_f32 v[126:127], v[126:127], 1.0 op_sel_hi:[1,0]
	v_mul_f32_e32 v144, v143, v142
	v_mul_f32_e32 v145, v127, v126
	v_or_b32_e32 v148, 16, v197
	v_mul_f32_e32 v146, v144, v145
	v_rcp_f32_e32 v147, v146
	v_pk_mul_f32 v[108:109], v[108:109], v[202:203] op_sel_hi:[1,0]
	v_pk_mul_f32 v[110:111], v[110:111], v[202:203] op_sel_hi:[1,0]
	v_pk_mul_f32 v[106:107], v[106:107], v[202:203] op_sel_hi:[1,0]
	v_mul_f32_e32 v144, v144, v147
	v_mul_f32_e32 v146, v145, v147
	v_pk_mul_f32 v[126:127], v[126:127], v[144:145] op_sel_hi:[1,0]
	v_pk_mul_f32 v[142:143], v[142:143], v[146:147] op_sel_hi:[1,0]
	v_pk_mul_f32 v[122:123], v[122:123], v[126:127]
	v_pk_mul_f32 v[120:121], v[120:121], v[142:143]
	v_mov_b32_dpp v126, v160 row_ror:1 row_mask:0xf bank_mask:0xf
	v_mov_b32_dpp v127, v161 row_ror:1 row_mask:0xf bank_mask:0xf
	v_pk_mul_f32 v[122:123], v[138:139], v[122:123]
	v_pk_mul_f32 v[120:121], v[140:141], v[120:121]
	v_mov_b32_dpp v126, v174 row_shr:1 row_mask:0xf bank_mask:0xf
	v_mov_b32_dpp v127, v175 row_shr:1 row_mask:0xf bank_mask:0xf
	v_mov_b32_dpp v138, v162 row_ror:1 row_mask:0xf bank_mask:0xf
	v_mov_b32_dpp v139, v163 row_ror:1 row_mask:0xf bank_mask:0xf
	v_mov_b32_dpp v140, v116 row_ror:15 row_mask:0xf bank_mask:0xf
	v_mov_b32_dpp v141, v117 row_ror:15 row_mask:0xf bank_mask:0xf
	v_pk_fma_f32 v[126:127], v[64:65], v[126:127], v[68:69]
	v_mov_b32_dpp v138, v172 row_shr:1 row_mask:0xf bank_mask:0xf
	v_mov_b32_dpp v139, v173 row_shr:1 row_mask:0xf bank_mask:0xf
	v_mov_b32_dpp v140, v174 row_shl:1 row_mask:0xf bank_mask:0xf
	v_mov_b32_dpp v141, v175 row_shl:1 row_mask:0xf bank_mask:0xf
	v_pk_fma_f32 v[126:127], v[174:175], v[60:61], v[126:127]
	v_mov_b32_dpp v142, v114 row_ror:15 row_mask:0xf bank_mask:0xf
	v_mov_b32_dpp v143, v115 row_ror:15 row_mask:0xf bank_mask:0xf
	v_pk_fma_f32 v[138:139], v[66:67], v[138:139], v[70:71]
	v_pk_fma_f32 v[126:127], v[56:57], v[140:141], v[126:127]
	v_mov_b32_dpp v142, v172 row_shl:1 row_mask:0xf bank_mask:0xf
	v_mov_b32_dpp v143, v173 row_shl:1 row_mask:0xf bank_mask:0xf
	v_pk_fma_f32 v[138:139], v[172:173], v[62:63], v[138:139]
	v_pk_mul_f32 v[140:141], v[126:127], v[126:127]
	v_pk_fma_f32 v[138:139], v[58:59], v[142:143], v[138:139]
	v_pk_mul_f32 v[140:141], v[126:127], v[140:141]
	v_pk_mul_f32 v[142:143], v[138:139], v[138:139]
	v_pk_fma_f32 v[140:141], v[140:141], s[70:71], v[126:127] op_sel_hi:[1,0,1]
	v_pk_mul_f32 v[142:143], v[138:139], v[142:143]
	v_pk_mul_f32 v[140:141], v[140:141], s[72:73] op_sel_hi:[1,0]
	v_pk_fma_f32 v[142:143], v[142:143], s[70:71], v[138:139] op_sel_hi:[1,0,1]
	v_min_f32_e32 v140, 0x41e6d4ca, v140
	v_pk_mul_f32 v[142:143], v[142:143], s[72:73] op_sel_hi:[1,0]
	v_exp_f32_e32 v145, v140
	v_min_f32_e32 v140, 0x41e6d4ca, v141
	v_exp_f32_e32 v144, v140
	v_min_f32_e32 v140, 0x41e6d4ca, v142
	v_exp_f32_e32 v141, v140
	v_min_f32_e32 v140, 0x41e6d4ca, v143
	v_exp_f32_e32 v140, v140
	v_pk_add_f32 v[142:143], v[144:145], 1.0 op_sel_hi:[1,0]
	v_pk_mul_f32 v[104:105], v[104:105], v[202:203] op_sel_hi:[1,0]
	v_pk_add_f32 v[140:141], v[140:141], 1.0 op_sel_hi:[1,0]
	v_mul_f32_e32 v144, v143, v142
	v_mul_f32_e32 v145, v141, v140
	v_mov_b32_dpp v156, v132 row_shl:1 row_mask:0xf bank_mask:0xf
	v_mul_f32_e32 v146, v144, v145
	v_rcp_f32_e32 v147, v146
	v_mov_b32_dpp v157, v133 row_shl:1 row_mask:0xf bank_mask:0xf
	v_mov_b32_dpp v158, v134 row_shl:1 row_mask:0xf bank_mask:0xf
	v_mov_b32_dpp v159, v135 row_shl:1 row_mask:0xf bank_mask:0xf
	v_mul_f32_e32 v146, v145, v147
	v_mul_f32_e32 v144, v144, v147
	v_pk_mul_f32 v[140:141], v[140:141], v[144:145] op_sel_hi:[1,0]
	v_pk_mul_f32 v[142:143], v[142:143], v[146:147] op_sel_hi:[1,0]
	v_pk_mul_f32 v[138:139], v[138:139], v[140:141]
	v_pk_mul_f32 v[126:127], v[126:127], v[142:143]
	v_pk_mul_f32 v[140:141], v[136:137], v[138:139]
	v_pk_mul_f32 v[112:113], v[112:113], v[126:127]
	v_cvt_pk_bf16_f32 v136, v120, v121
	v_mov_b64_e32 v[120:121], s[86:87]
	v_cvt_pk_bf16_f32 v137, v122, v123
	v_cvt_pk_bf16_f32 v138, v112, v113
	v_mad_i64_i32 v[122:123], s[10:11], v148, s90, v[120:121]
	v_lshlrev_b64 v[112:113], 1, v[192:193]
	v_cvt_pk_bf16_f32 v139, v140, v141
	v_lshl_add_u64 v[122:123], v[122:123], 0, v[112:113]
	global_store_dwordx4 v[122:123], v[136:139], off
	s_nop 0
	v_mov_b32_dpp v122, v210 row_ror:1 row_mask:0xf bank_mask:0xf
	v_mov_b32_dpp v123, v211 row_ror:1 row_mask:0xf bank_mask:0xf
	s_nop 0
	v_mov_b32_dpp v122, v124 row_shr:1 row_mask:0xf bank_mask:0xf
	v_mov_b32_dpp v123, v125 row_shr:1 row_mask:0xf bank_mask:0xf
	v_mov_b32_dpp v126, v206 row_ror:1 row_mask:0xf bank_mask:0xf
	v_mov_b32_dpp v127, v207 row_ror:1 row_mask:0xf bank_mask:0xf
	v_mov_b32_dpp v136, v132 row_ror:15 row_mask:0xf bank_mask:0xf
	v_mov_b32_dpp v137, v133 row_ror:15 row_mask:0xf bank_mask:0xf
	v_pk_fma_f32 v[122:123], v[80:81], v[122:123], v[84:85]
	v_mov_b32_dpp v126, v118 row_shr:1 row_mask:0xf bank_mask:0xf
	v_mov_b32_dpp v127, v119 row_shr:1 row_mask:0xf bank_mask:0xf
	v_mov_b32_dpp v136, v124 row_shl:1 row_mask:0xf bank_mask:0xf
	v_mov_b32_dpp v137, v125 row_shl:1 row_mask:0xf bank_mask:0xf
	v_pk_fma_f32 v[122:123], v[124:125], v[76:77], v[122:123]
	v_mov_b32_dpp v138, v134 row_ror:15 row_mask:0xf bank_mask:0xf
	v_mov_b32_dpp v139, v135 row_ror:15 row_mask:0xf bank_mask:0xf
	v_pk_fma_f32 v[126:127], v[82:83], v[126:127], v[86:87]
	v_pk_fma_f32 v[122:123], v[72:73], v[136:137], v[122:123]
	v_mov_b32_dpp v138, v118 row_shl:1 row_mask:0xf bank_mask:0xf
	v_mov_b32_dpp v139, v119 row_shl:1 row_mask:0xf bank_mask:0xf
	v_pk_fma_f32 v[126:127], v[118:119], v[78:79], v[126:127]
	v_pk_mul_f32 v[136:137], v[122:123], v[122:123]
	v_pk_fma_f32 v[126:127], v[74:75], v[138:139], v[126:127]
	v_pk_mul_f32 v[136:137], v[122:123], v[136:137]
	v_pk_mul_f32 v[138:139], v[126:127], v[126:127]
	v_pk_fma_f32 v[136:137], v[136:137], s[70:71], v[122:123] op_sel_hi:[1,0,1]
	v_pk_mul_f32 v[138:139], v[126:127], v[138:139]
	v_pk_mul_f32 v[136:137], v[136:137], s[72:73] op_sel_hi:[1,0]
	v_pk_fma_f32 v[138:139], v[138:139], s[70:71], v[126:127] op_sel_hi:[1,0,1]
	v_min_f32_e32 v136, 0x41e6d4ca, v136
	v_pk_mul_f32 v[138:139], v[138:139], s[72:73] op_sel_hi:[1,0]
	v_exp_f32_e32 v141, v136
	v_min_f32_e32 v136, 0x41e6d4ca, v137
	v_exp_f32_e32 v140, v136
	v_min_f32_e32 v136, 0x41e6d4ca, v138
	v_exp_f32_e32 v137, v136
	v_min_f32_e32 v136, 0x41e6d4ca, v139
	v_exp_f32_e32 v136, v136
	v_pk_add_f32 v[138:139], v[140:141], 1.0 op_sel_hi:[1,0]
	v_or_b32_e32 v144, 32, v197
	v_pk_add_f32 v[136:137], v[136:137], 1.0 op_sel_hi:[1,0]
	v_mul_f32_e32 v140, v139, v138
	v_mul_f32_e32 v141, v137, v136
	v_pk_mul_f32 v[100:101], v[100:101], v[204:205]
	v_mul_f32_e32 v142, v140, v141
	v_rcp_f32_e32 v143, v142
	v_mov_b32_dpp v152, v128 row_shl:1 row_mask:0xf bank_mask:0xf
	v_mov_b32_dpp v153, v129 row_shl:1 row_mask:0xf bank_mask:0xf
	v_mov_b32_dpp v154, v130 row_shl:1 row_mask:0xf bank_mask:0xf
	v_mul_f32_e32 v142, v141, v143
	v_pk_mul_f32 v[138:139], v[138:139], v[142:143] op_sel_hi:[1,0]
	v_mul_f32_e32 v140, v140, v143
	v_pk_mul_f32 v[122:123], v[122:123], v[138:139]
	v_pk_mul_f32 v[136:137], v[136:137], v[140:141] op_sel_hi:[1,0]
	v_pk_mul_f32 v[108:109], v[108:109], v[122:123]
	v_pk_mul_f32 v[126:127], v[126:127], v[136:137]
	v_mov_b32_dpp v122, v174 row_ror:1 row_mask:0xf bank_mask:0xf
	v_mov_b32_dpp v123, v175 row_ror:1 row_mask:0xf bank_mask:0xf
	v_pk_mul_f32 v[110:111], v[110:111], v[126:127]
	v_mov_b32_dpp v122, v116 row_shr:1 row_mask:0xf bank_mask:0xf
	v_mov_b32_dpp v123, v117 row_shr:1 row_mask:0xf bank_mask:0xf
	v_mov_b32_dpp v126, v172 row_ror:1 row_mask:0xf bank_mask:0xf
	v_mov_b32_dpp v127, v173 row_ror:1 row_mask:0xf bank_mask:0xf
	v_mov_b32_dpp v136, v128 row_ror:15 row_mask:0xf bank_mask:0xf
	v_mov_b32_dpp v137, v129 row_ror:15 row_mask:0xf bank_mask:0xf
	v_pk_fma_f32 v[122:123], v[64:65], v[122:123], v[68:69]
	v_mov_b32_dpp v126, v114 row_shr:1 row_mask:0xf bank_mask:0xf
	v_mov_b32_dpp v127, v115 row_shr:1 row_mask:0xf bank_mask:0xf
	v_mov_b32_dpp v136, v116 row_shl:1 row_mask:0xf bank_mask:0xf
	v_mov_b32_dpp v137, v117 row_shl:1 row_mask:0xf bank_mask:0xf
	v_pk_fma_f32 v[122:123], v[116:117], v[60:61], v[122:123]
	v_mov_b32_dpp v138, v130 row_ror:15 row_mask:0xf bank_mask:0xf
	v_mov_b32_dpp v139, v131 row_ror:15 row_mask:0xf bank_mask:0xf
	v_pk_fma_f32 v[126:127], v[66:67], v[126:127], v[70:71]
	v_pk_fma_f32 v[122:123], v[56:57], v[136:137], v[122:123]
	v_mov_b32_dpp v138, v114 row_shl:1 row_mask:0xf bank_mask:0xf
	v_mov_b32_dpp v139, v115 row_shl:1 row_mask:0xf bank_mask:0xf
	v_pk_fma_f32 v[126:127], v[114:115], v[62:63], v[126:127]
	v_pk_mul_f32 v[136:137], v[122:123], v[122:123]
	v_pk_fma_f32 v[126:127], v[58:59], v[138:139], v[126:127]
	v_pk_mul_f32 v[136:137], v[122:123], v[136:137]
	v_pk_mul_f32 v[138:139], v[126:127], v[126:127]
	v_pk_fma_f32 v[136:137], v[136:137], s[70:71], v[122:123] op_sel_hi:[1,0,1]
	v_pk_mul_f32 v[138:139], v[126:127], v[138:139]
	v_pk_mul_f32 v[136:137], v[136:137], s[72:73] op_sel_hi:[1,0]
	v_pk_fma_f32 v[138:139], v[138:139], s[70:71], v[126:127] op_sel_hi:[1,0,1]
	v_min_f32_e32 v136, 0x41e6d4ca, v136
	v_pk_mul_f32 v[138:139], v[138:139], s[72:73] op_sel_hi:[1,0]
	v_exp_f32_e32 v141, v136
	v_min_f32_e32 v136, 0x41e6d4ca, v137
	v_exp_f32_e32 v140, v136
	v_min_f32_e32 v136, 0x41e6d4ca, v138
	v_exp_f32_e32 v137, v136
	v_min_f32_e32 v136, 0x41e6d4ca, v139
	v_exp_f32_e32 v136, v136
	v_pk_add_f32 v[138:139], v[140:141], 1.0 op_sel_hi:[1,0]
	v_mov_b32_dpp v155, v131 row_shl:1 row_mask:0xf bank_mask:0xf
	v_pk_add_f32 v[136:137], v[136:137], 1.0 op_sel_hi:[1,0]
	v_mul_f32_e32 v140, v139, v138
	v_mul_f32_e32 v141, v137, v136
	v_pk_mul_f32 v[96:97], v[96:97], v[204:205]
	v_mul_f32_e32 v142, v140, v141
	v_rcp_f32_e32 v143, v142
	s_or_b32 s14, s12, 1
	s_mul_hi_i32 s12, s14, 0x8400
	s_mul_i32 s14, s14, 0x8400
	v_mul_f32_e32 v142, v141, v143
	v_mul_f32_e32 v140, v140, v143
	v_pk_mul_f32 v[136:137], v[136:137], v[140:141] op_sel_hi:[1,0]
	v_pk_mul_f32 v[138:139], v[138:139], v[142:143] op_sel_hi:[1,0]
	v_pk_mul_f32 v[126:127], v[126:127], v[136:137]
	v_pk_mul_f32 v[122:123], v[122:123], v[138:139]
	v_pk_mul_f32 v[126:127], v[106:107], v[126:127]
	v_pk_mul_f32 v[106:107], v[104:105], v[122:123]
	v_cvt_pk_bf16_f32 v104, v108, v109
	v_mad_i64_i32 v[108:109], s[10:11], v144, s90, v[120:121]
	v_cvt_pk_bf16_f32 v105, v110, v111
	v_cvt_pk_bf16_f32 v106, v106, v107
	v_cvt_pk_bf16_f32 v107, v126, v127
	v_lshl_add_u64 v[108:109], v[108:109], 0, v[112:113]
	global_store_dwordx4 v[108:109], v[104:107], off
	v_or_b32_e32 v136, 48, v197
	s_nop 0
	v_mov_b32_dpp v104, v124 row_ror:1 row_mask:0xf bank_mask:0xf
	v_mov_b32_dpp v105, v125 row_ror:1 row_mask:0xf bank_mask:0xf
	s_nop 0
	v_mov_b32_dpp v104, v132 row_shr:1 row_mask:0xf bank_mask:0xf
	v_mov_b32_dpp v105, v133 row_shr:1 row_mask:0xf bank_mask:0xf
	v_mov_b32_dpp v106, v118 row_ror:1 row_mask:0xf bank_mask:0xf
	v_mov_b32_dpp v107, v119 row_ror:1 row_mask:0xf bank_mask:0xf
	v_pk_fma_f32 v[104:105], v[80:81], v[104:105], v[84:85]
	v_mov_b32_dpp v106, v134 row_shr:1 row_mask:0xf bank_mask:0xf
	v_mov_b32_dpp v107, v135 row_shr:1 row_mask:0xf bank_mask:0xf
	v_pk_fma_f32 v[104:105], v[132:133], v[76:77], v[104:105]
	v_pk_fma_f32 v[106:107], v[82:83], v[106:107], v[86:87]
	v_pk_fma_f32 v[104:105], v[72:73], v[156:157], v[104:105]
	v_pk_fma_f32 v[106:107], v[134:135], v[78:79], v[106:107]
	v_pk_mul_f32 v[108:109], v[104:105], v[104:105]
	v_pk_fma_f32 v[106:107], v[74:75], v[158:159], v[106:107]
	v_pk_mul_f32 v[108:109], v[104:105], v[108:109]
	v_pk_mul_f32 v[110:111], v[106:107], v[106:107]
	v_pk_fma_f32 v[108:109], v[108:109], s[70:71], v[104:105] op_sel_hi:[1,0,1]
	v_pk_mul_f32 v[110:111], v[106:107], v[110:111]
	v_pk_mul_f32 v[108:109], v[108:109], s[72:73] op_sel_hi:[1,0]
	v_pk_fma_f32 v[110:111], v[110:111], s[70:71], v[106:107] op_sel_hi:[1,0,1]
	v_min_f32_e32 v108, 0x41e6d4ca, v108
	v_pk_mul_f32 v[110:111], v[110:111], s[72:73] op_sel_hi:[1,0]
	v_exp_f32_e32 v119, v108
	v_min_f32_e32 v108, 0x41e6d4ca, v109
	v_exp_f32_e32 v118, v108
	v_min_f32_e32 v108, 0x41e6d4ca, v110
	v_exp_f32_e32 v109, v108
	v_min_f32_e32 v108, 0x41e6d4ca, v111
	v_exp_f32_e32 v108, v108
	v_pk_add_f32 v[110:111], v[118:119], 1.0 op_sel_hi:[1,0]
	v_pk_add_f32 v[108:109], v[108:109], 1.0 op_sel_hi:[1,0]
	v_mul_f32_e32 v118, v111, v110
	v_mul_f32_e32 v119, v109, v108
	s_nop 0
	v_mul_f32_e32 v122, v118, v119
	v_rcp_f32_e32 v123, v122
	s_nop 0
	v_mul_f32_e32 v118, v118, v123
	v_pk_mul_f32 v[108:109], v[108:109], v[118:119] op_sel_hi:[1,0]
	v_mul_f32_e32 v122, v119, v123
	v_pk_mul_f32 v[108:109], v[106:107], v[108:109]
	v_pk_mul_f32 v[110:111], v[110:111], v[122:123] op_sel_hi:[1,0]
	v_pk_mul_f32 v[118:119], v[102:103], v[108:109]
	v_pk_mul_f32 v[110:111], v[104:105], v[110:111]
	v_mov_b32_dpp v108, v116 row_ror:1 row_mask:0xf bank_mask:0xf
	v_mov_b32_dpp v109, v117 row_ror:1 row_mask:0xf bank_mask:0xf
	v_pk_mul_f32 v[122:123], v[100:101], v[110:111]
	v_mov_b32_dpp v108, v128 row_shr:1 row_mask:0xf bank_mask:0xf
	v_mov_b32_dpp v109, v129 row_shr:1 row_mask:0xf bank_mask:0xf
	v_mov_b32_dpp v110, v114 row_ror:1 row_mask:0xf bank_mask:0xf
	v_mov_b32_dpp v111, v115 row_ror:1 row_mask:0xf bank_mask:0xf
	v_pk_fma_f32 v[108:109], v[64:65], v[108:109], v[68:69]
	v_mov_b32_dpp v110, v130 row_shr:1 row_mask:0xf bank_mask:0xf
	v_mov_b32_dpp v111, v131 row_shr:1 row_mask:0xf bank_mask:0xf
	v_pk_fma_f32 v[108:109], v[128:129], v[60:61], v[108:109]
	v_pk_fma_f32 v[110:111], v[66:67], v[110:111], v[70:71]
	v_pk_fma_f32 v[108:109], v[56:57], v[152:153], v[108:109]
	v_pk_fma_f32 v[110:111], v[130:131], v[62:63], v[110:111]
	v_pk_mul_f32 v[114:115], v[108:109], v[108:109]
	v_pk_fma_f32 v[110:111], v[58:59], v[154:155], v[110:111]
	v_pk_mul_f32 v[114:115], v[108:109], v[114:115]
	v_pk_mul_f32 v[116:117], v[110:111], v[110:111]
	v_pk_fma_f32 v[114:115], v[114:115], s[70:71], v[108:109] op_sel_hi:[1,0,1]
	v_pk_mul_f32 v[116:117], v[110:111], v[116:117]
	v_pk_mul_f32 v[114:115], v[114:115], s[72:73] op_sel_hi:[1,0]
	v_pk_fma_f32 v[116:117], v[116:117], s[70:71], v[110:111] op_sel_hi:[1,0,1]
	v_min_f32_e32 v114, 0x41e6d4ca, v114
	v_pk_mul_f32 v[116:117], v[116:117], s[72:73] op_sel_hi:[1,0]
	v_exp_f32_e32 v125, v114
	v_min_f32_e32 v114, 0x41e6d4ca, v115
	v_exp_f32_e32 v124, v114
	v_min_f32_e32 v114, 0x41e6d4ca, v116
	v_exp_f32_e32 v115, v114
	v_min_f32_e32 v114, 0x41e6d4ca, v117
	v_exp_f32_e32 v114, v114
	v_pk_add_f32 v[116:117], v[124:125], 1.0 op_sel_hi:[1,0]
	v_pk_add_f32 v[114:115], v[114:115], 1.0 op_sel_hi:[1,0]
	v_mul_f32_e32 v124, v117, v116
	v_mul_f32_e32 v125, v115, v114
	s_nop 0
	v_mul_f32_e32 v126, v124, v125
	v_rcp_f32_e32 v127, v126
	s_nop 0
	v_mul_f32_e32 v126, v125, v127
	v_mul_f32_e32 v124, v124, v127
	v_pk_mul_f32 v[114:115], v[114:115], v[124:125] op_sel_hi:[1,0]
	v_pk_mul_f32 v[116:117], v[116:117], v[126:127] op_sel_hi:[1,0]
	v_pk_mul_f32 v[114:115], v[110:111], v[114:115]
	v_pk_mul_f32 v[116:117], v[108:109], v[116:117]
	v_pk_mul_f32 v[124:125], v[98:99], v[114:115]
	v_pk_mul_f32 v[116:117], v[96:97], v[116:117]
	v_cvt_pk_bf16_f32 v115, v118, v119
	v_mad_i64_i32 v[118:119], s[10:11], v136, s90, v[120:121]
	v_cvt_pk_bf16_f32 v114, v122, v123
	v_cvt_pk_bf16_f32 v116, v116, v117
	v_cvt_pk_bf16_f32 v117, v124, v125
	v_lshl_add_u64 v[118:119], v[118:119], 0, v[112:113]
	global_store_dwordx4 v[118:119], v[114:117], off
	s_and_saveexec_b64 s[10:11], s[58:59]
	s_cbranch_execz .LBB0_772
	s_add_u32 s24, s4, s14
	s_addc_u32 s25, s5, s12
	v_lshl_add_u64 v[114:115], v[192:193], 2, s[24:25]
	global_store_dwordx4 v[114:115], v[104:107], off
	s_nop 1
	v_add_co_u32_e32 v104, vcc, 0x2000, v114
	s_nop 1
	v_addc_co_u32_e32 v105, vcc, 0, v115, vcc
	v_add_co_u32_e32 v106, vcc, 0x5000, v114
	global_store_dwordx4 v[104:105], v[132:135], off offset:3072
	s_nop 0
	v_addc_co_u32_e32 v107, vcc, 0, v115, vcc
	global_store_dwordx4 v[106:107], v[100:103], off offset:2048
	global_store_dwordx4 v[114:115], v[108:111], off offset:16
	global_store_dwordx4 v[104:105], v[128:131], off offset:3088
	global_store_dwordx4 v[106:107], v[96:99], off offset:2064

.LBB0_780:
	v_pk_mul_f32 v[116:117], v[52:53], v[198:199] op_sel_hi:[1,0]
	s_waitcnt lgkmcnt(0)
	v_mov_b32_dpp v108, v92 row_shr:1 row_mask:0xf bank_mask:0xf
	v_mov_b32_dpp v109, v93 row_shr:1 row_mask:0xf bank_mask:0xf
	v_mov_b32_dpp v52, v116 row_ror:15 row_mask:0xf bank_mask:0xf
	v_mov_b32_dpp v53, v117 row_ror:15 row_mask:0xf bank_mask:0xf
	v_pk_fma_f32 v[108:109], v[80:81], v[108:109], v[84:85]
	v_pk_mul_f32 v[114:115], v[54:55], v[198:199] op_sel_hi:[1,0]
	v_mov_b32_dpp v110, v94 row_shr:1 row_mask:0xf bank_mask:0xf
	v_mov_b32_dpp v111, v95 row_shr:1 row_mask:0xf bank_mask:0xf
	v_mov_b32_dpp v52, v92 row_shl:1 row_mask:0xf bank_mask:0xf
	v_mov_b32_dpp v53, v93 row_shl:1 row_mask:0xf bank_mask:0xf
	v_pk_fma_f32 v[108:109], v[92:93], v[76:77], v[108:109]
	v_mov_b32_dpp v54, v114 row_ror:15 row_mask:0xf bank_mask:0xf
	v_mov_b32_dpp v55, v115 row_ror:15 row_mask:0xf bank_mask:0xf
	v_pk_fma_f32 v[110:111], v[82:83], v[110:111], v[86:87]
	v_pk_fma_f32 v[52:53], v[72:73], v[52:53], v[108:109]
	v_mov_b32_dpp v54, v94 row_shl:1 row_mask:0xf bank_mask:0xf
	v_mov_b32_dpp v55, v95 row_shl:1 row_mask:0xf bank_mask:0xf
	v_pk_fma_f32 v[110:111], v[94:95], v[78:79], v[110:111]
	v_pk_mul_f32 v[108:109], v[52:53], v[52:53]
	v_pk_fma_f32 v[54:55], v[74:75], v[54:55], v[110:111]
	v_pk_mul_f32 v[108:109], v[52:53], v[108:109]
	v_pk_mul_f32 v[110:111], v[54:55], v[54:55]
	v_pk_fma_f32 v[108:109], v[108:109], s[70:71], v[52:53] op_sel_hi:[1,0,1]
	v_pk_mul_f32 v[110:111], v[54:55], v[110:111]
	v_pk_mul_f32 v[108:109], v[108:109], s[72:73] op_sel_hi:[1,0]
	v_pk_fma_f32 v[110:111], v[110:111], s[70:71], v[54:55] op_sel_hi:[1,0,1]
	v_min_f32_e32 v108, 0x41e6d4ca, v108
	v_pk_mul_f32 v[110:111], v[110:111], s[72:73] op_sel_hi:[1,0]
	v_exp_f32_e32 v121, v108
	v_min_f32_e32 v108, 0x41e6d4ca, v109
	v_exp_f32_e32 v120, v108
	v_min_f32_e32 v108, 0x41e6d4ca, v110
	v_exp_f32_e32 v109, v108
	v_min_f32_e32 v108, 0x41e6d4ca, v111
	v_exp_f32_e32 v108, v108
	v_pk_mul_f32 v[50:51], v[50:51], v[200:201] op_sel_hi:[1,0]
	v_pk_mul_f32 v[42:43], v[42:43], v[200:201] op_sel_hi:[1,0]
	v_pk_add_f32 v[118:119], v[120:121], 1.0 op_sel_hi:[1,0]
	v_pk_add_f32 v[120:121], v[108:109], 1.0 op_sel_hi:[1,0]
	v_mul_f32_e32 v122, v119, v118
	v_mul_f32_e32 v123, v121, v120
	v_pk_mul_f32 v[110:111], v[44:45], v[198:199] op_sel_hi:[1,0]
	v_mul_f32_e32 v108, v122, v123
	v_rcp_f32_e32 v125, v108
	v_mov_b32_dpp v104, v88 row_shr:1 row_mask:0xf bank_mask:0xf
	v_mov_b32_dpp v105, v89 row_shr:1 row_mask:0xf bank_mask:0xf
	v_pk_fma_f32 v[104:105], v[64:65], v[104:105], v[68:69]
	v_mul_f32_e32 v44, v122, v125
	v_pk_mul_f32 v[120:121], v[120:121], v[44:45] op_sel_hi:[1,0]
	v_pk_mul_f32 v[108:109], v[46:47], v[198:199] op_sel_hi:[1,0]
	v_mov_b32_dpp v44, v110 row_ror:15 row_mask:0xf bank_mask:0xf
	v_mov_b32_dpp v45, v111 row_ror:15 row_mask:0xf bank_mask:0xf
	v_mov_b32_dpp v106, v90 row_shr:1 row_mask:0xf bank_mask:0xf
	v_mov_b32_dpp v107, v91 row_shr:1 row_mask:0xf bank_mask:0xf
	v_mov_b32_dpp v44, v88 row_shl:1 row_mask:0xf bank_mask:0xf
	v_mov_b32_dpp v45, v89 row_shl:1 row_mask:0xf bank_mask:0xf
	v_pk_fma_f32 v[104:105], v[88:89], v[60:61], v[104:105]
	v_mov_b32_dpp v46, v108 row_ror:15 row_mask:0xf bank_mask:0xf
	v_mov_b32_dpp v47, v109 row_ror:15 row_mask:0xf bank_mask:0xf
	v_pk_fma_f32 v[106:107], v[66:67], v[106:107], v[70:71]
	v_pk_fma_f32 v[44:45], v[56:57], v[44:45], v[104:105]
	v_mov_b32_dpp v46, v90 row_shl:1 row_mask:0xf bank_mask:0xf
	v_mov_b32_dpp v47, v91 row_shl:1 row_mask:0xf bank_mask:0xf
	v_pk_fma_f32 v[106:107], v[90:91], v[62:63], v[106:107]
	v_pk_mul_f32 v[104:105], v[44:45], v[44:45]
	v_pk_fma_f32 v[46:47], v[58:59], v[46:47], v[106:107]
	v_pk_mul_f32 v[104:105], v[44:45], v[104:105]
	v_pk_mul_f32 v[106:107], v[46:47], v[46:47]
	v_pk_fma_f32 v[104:105], v[104:105], s[70:71], v[44:45] op_sel_hi:[1,0,1]
	v_pk_mul_f32 v[106:107], v[46:47], v[106:107]
	v_pk_mul_f32 v[104:105], v[104:105], s[72:73] op_sel_hi:[1,0]
	v_pk_fma_f32 v[106:107], v[106:107], s[70:71], v[46:47] op_sel_hi:[1,0,1]
	v_min_f32_e32 v104, 0x41e6d4ca, v104
	v_mul_f32_e32 v124, v123, v125
	v_pk_mul_f32 v[106:107], v[106:107], s[72:73] op_sel_hi:[1,0]
	v_exp_f32_e32 v123, v104
	v_min_f32_e32 v104, 0x41e6d4ca, v105
	v_exp_f32_e32 v122, v104
	v_min_f32_e32 v104, 0x41e6d4ca, v106
	v_exp_f32_e32 v105, v104
	v_min_f32_e32 v104, 0x41e6d4ca, v107
	v_exp_f32_e32 v104, v104
	v_pk_mul_f32 v[106:107], v[118:119], v[124:125] op_sel_hi:[1,0]
	v_pk_add_f32 v[118:119], v[122:123], 1.0 op_sel_hi:[1,0]
	v_pk_mul_f32 v[48:49], v[48:49], v[200:201]
	v_pk_add_f32 v[104:105], v[104:105], 1.0 op_sel_hi:[1,0]
	v_mul_f32_e32 v122, v119, v118
	v_mul_f32_e32 v123, v105, v104
	v_pk_mul_f32 v[40:41], v[40:41], v[200:201]
	v_mul_f32_e32 v124, v122, v123
	v_rcp_f32_e32 v125, v124
	v_pk_mul_f32 v[106:107], v[52:53], v[106:107]
	v_add_u32_e32 v126, 0x80, v197
	v_pk_mul_f32 v[106:107], v[48:49], v[106:107]
	v_mul_f32_e32 v124, v123, v125
	v_mul_f32_e32 v122, v122, v125
	v_pk_mul_f32 v[118:119], v[118:119], v[124:125] op_sel_hi:[1,0]
	v_pk_mul_f32 v[104:105], v[104:105], v[122:123] op_sel_hi:[1,0]
	v_pk_mul_f32 v[118:119], v[44:45], v[118:119]
	v_pk_mul_f32 v[104:105], v[46:47], v[104:105]
	v_pk_mul_f32 v[118:119], v[40:41], v[118:119]
	v_pk_mul_f32 v[120:121], v[54:55], v[120:121]
	v_pk_mul_f32 v[122:123], v[42:43], v[104:105]
	v_cvt_pk_bf16_f32 v104, v106, v107
	v_cvt_pk_bf16_f32 v106, v118, v119
	v_mov_b64_e32 v[118:119], s[86:87]
	v_pk_mul_f32 v[120:121], v[50:51], v[120:121]
	v_mad_i64_i32 v[118:119], s[10:11], v126, s90, v[118:119]
	v_cvt_pk_bf16_f32 v105, v120, v121
	v_cvt_pk_bf16_f32 v107, v122, v123
	v_lshl_add_u64 v[118:119], v[192:193], 1, v[118:119]
	global_store_dwordx4 v[118:119], v[104:107], off
	s_and_saveexec_b64 s[10:11], s[42:43]
	s_cbranch_execz .LBB0_782
	s_add_u32 s24, s4, s15
	s_addc_u32 s25, s5, s16
	v_lshl_add_u64 v[104:105], v[192:193], 2, s[24:25]
	global_store_dwordx4 v[104:105], v[52:55], off
	s_nop 1
	v_add_co_u32_e32 v52, vcc, 0x2000, v104
	s_nop 1
	v_addc_co_u32_e32 v53, vcc, 0, v105, vcc
	v_add_co_u32_e32 v54, vcc, 0x5000, v104
	global_store_dwordx4 v[52:53], v[92:95], off offset:3072
	s_nop 0
	v_addc_co_u32_e32 v55, vcc, 0, v105, vcc
	global_store_dwordx4 v[54:55], v[48:51], off offset:2048
	global_store_dwordx4 v[104:105], v[44:47], off offset:16
	global_store_dwordx4 v[52:53], v[88:91], off offset:3088
	global_store_dwordx4 v[54:55], v[40:43], off offset:2064
.LBB0_782:
	s_or_b64 exec, exec, s[10:11]
	s_nop 0
	v_pk_mul_f32 v[44:45], v[22:23], v[198:199] op_sel_hi:[1,0]
	v_pk_mul_f32 v[40:41], v[18:19], v[198:199] op_sel_hi:[1,0]
	v_pk_mul_f32 v[18:19], v[24:25], v[196:197] op_sel_hi:[1,0]
	v_pk_mul_f32 v[6:7], v[6:7], v[194:195] op_sel_hi:[1,0]
	v_pk_mul_f32 v[2:3], v[2:3], v[194:195] op_sel_hi:[1,0]
	v_mov_b32_dpp v24, v92 row_ror:1 row_mask:0xf bank_mask:0xf
	v_mov_b32_dpp v25, v93 row_ror:1 row_mask:0xf bank_mask:0xf
	v_pk_mul_f32 v[42:43], v[16:17], v[198:199] op_sel_hi:[1,0]
	v_pk_mul_f32 v[22:23], v[28:29], v[196:197] op_sel_hi:[1,0]
	v_pk_mul_f32 v[16:17], v[26:27], v[196:197] op_sel_hi:[1,0]
	v_mov_b32_dpp v24, v116 row_shr:1 row_mask:0xf bank_mask:0xf
	v_mov_b32_dpp v25, v117 row_shr:1 row_mask:0xf bank_mask:0xf
	v_mov_b32_dpp v26, v94 row_ror:1 row_mask:0xf bank_mask:0xf
	v_mov_b32_dpp v27, v95 row_ror:1 row_mask:0xf bank_mask:0xf
	v_mov_b32_dpp v28, v22 row_ror:15 row_mask:0xf bank_mask:0xf
	v_mov_b32_dpp v29, v23 row_ror:15 row_mask:0xf bank_mask:0xf
	v_pk_fma_f32 v[24:25], v[80:81], v[24:25], v[84:85]
	v_pk_mul_f32 v[46:47], v[20:21], v[198:199] op_sel_hi:[1,0]
	v_pk_mul_f32 v[20:21], v[30:31], v[196:197] op_sel_hi:[1,0]
	v_mov_b32_dpp v26, v114 row_shr:1 row_mask:0xf bank_mask:0xf
	v_mov_b32_dpp v27, v115 row_shr:1 row_mask:0xf bank_mask:0xf
	v_mov_b32_dpp v28, v116 row_shl:1 row_mask:0xf bank_mask:0xf
	v_mov_b32_dpp v29, v117 row_shl:1 row_mask:0xf bank_mask:0xf
	v_pk_fma_f32 v[24:25], v[116:117], v[76:77], v[24:25]
	v_mov_b32_dpp v30, v20 row_ror:15 row_mask:0xf bank_mask:0xf
	v_mov_b32_dpp v31, v21 row_ror:15 row_mask:0xf bank_mask:0xf
	v_pk_fma_f32 v[26:27], v[82:83], v[26:27], v[86:87]
	v_pk_fma_f32 v[24:25], v[72:73], v[28:29], v[24:25]
	v_mov_b32_dpp v30, v114 row_shl:1 row_mask:0xf bank_mask:0xf
	v_mov_b32_dpp v31, v115 row_shl:1 row_mask:0xf bank_mask:0xf
	v_pk_fma_f32 v[26:27], v[114:115], v[78:79], v[26:27]
	v_pk_mul_f32 v[28:29], v[24:25], v[24:25]
	v_pk_fma_f32 v[26:27], v[74:75], v[30:31], v[26:27]
	v_pk_mul_f32 v[28:29], v[24:25], v[28:29]
	v_pk_mul_f32 v[30:31], v[26:27], v[26:27]
	v_pk_fma_f32 v[28:29], v[28:29], s[70:71], v[24:25] op_sel_hi:[1,0,1]
	v_pk_mul_f32 v[30:31], v[26:27], v[30:31]
	v_pk_mul_f32 v[28:29], v[28:29], s[72:73] op_sel_hi:[1,0]
	v_pk_fma_f32 v[30:31], v[30:31], s[70:71], v[26:27] op_sel_hi:[1,0,1]
	v_min_f32_e32 v28, 0x41e6d4ca, v28
	v_pk_mul_f32 v[30:31], v[30:31], s[72:73] op_sel_hi:[1,0]
	v_exp_f32_e32 v49, v28
	v_min_f32_e32 v28, 0x41e6d4ca, v29
	v_exp_f32_e32 v48, v28
	v_min_f32_e32 v28, 0x41e6d4ca, v30
	v_exp_f32_e32 v29, v28
	v_min_f32_e32 v28, 0x41e6d4ca, v31
	v_exp_f32_e32 v28, v28
	v_pk_add_f32 v[30:31], v[48:49], 1.0 op_sel_hi:[1,0]
	v_add_u32_e32 v52, 0x90, v197
	v_pk_add_f32 v[28:29], v[28:29], 1.0 op_sel_hi:[1,0]
	v_mul_f32_e32 v48, v31, v30
	v_mul_f32_e32 v49, v29, v28
	v_pk_mul_f32 v[12:13], v[12:13], v[196:197] op_sel_hi:[1,0]
	v_mul_f32_e32 v50, v48, v49
	v_rcp_f32_e32 v51, v50
	v_pk_mul_f32 v[14:15], v[14:15], v[196:197] op_sel_hi:[1,0]
	v_pk_mul_f32 v[10:11], v[10:11], v[196:197] op_sel_hi:[1,0]
	v_pk_mul_f32 v[8:9], v[8:9], v[196:197] op_sel_hi:[1,0]
	v_mul_f32_e32 v48, v48, v51
	v_pk_mul_f32 v[28:29], v[28:29], v[48:49] op_sel_hi:[1,0]
	v_mul_f32_e32 v50, v49, v51
	v_pk_mul_f32 v[26:27], v[26:27], v[28:29]
	v_pk_mul_f32 v[30:31], v[30:31], v[50:51] op_sel_hi:[1,0]
	v_pk_mul_f32 v[28:29], v[44:45], v[26:27]
	v_pk_mul_f32 v[24:25], v[24:25], v[30:31]
	v_mov_b32_dpp v26, v88 row_ror:1 row_mask:0xf bank_mask:0xf
	v_mov_b32_dpp v27, v89 row_ror:1 row_mask:0xf bank_mask:0xf
	s_nop 0
	v_mov_b32_dpp v26, v110 row_shr:1 row_mask:0xf bank_mask:0xf
	v_mov_b32_dpp v27, v111 row_shr:1 row_mask:0xf bank_mask:0xf
	v_mov_b32_dpp v30, v90 row_ror:1 row_mask:0xf bank_mask:0xf
	v_mov_b32_dpp v31, v91 row_ror:1 row_mask:0xf bank_mask:0xf
	v_mov_b32_dpp v44, v18 row_ror:15 row_mask:0xf bank_mask:0xf
	v_mov_b32_dpp v45, v19 row_ror:15 row_mask:0xf bank_mask:0xf
	v_pk_fma_f32 v[26:27], v[64:65], v[26:27], v[68:69]
	v_pk_mul_f32 v[24:25], v[46:47], v[24:25]
	v_mov_b32_dpp v30, v108 row_shr:1 row_mask:0xf bank_mask:0xf
	v_mov_b32_dpp v31, v109 row_shr:1 row_mask:0xf bank_mask:0xf
	v_mov_b32_dpp v44, v110 row_shl:1 row_mask:0xf bank_mask:0xf
	v_mov_b32_dpp v45, v111 row_shl:1 row_mask:0xf bank_mask:0xf
	v_pk_fma_f32 v[26:27], v[110:111], v[60:61], v[26:27]
	v_mov_b32_dpp v46, v16 row_ror:15 row_mask:0xf bank_mask:0xf
	v_mov_b32_dpp v47, v17 row_ror:15 row_mask:0xf bank_mask:0xf
	v_pk_fma_f32 v[30:31], v[66:67], v[30:31], v[70:71]
	v_pk_fma_f32 v[26:27], v[56:57], v[44:45], v[26:27]
	v_mov_b32_dpp v46, v108 row_shl:1 row_mask:0xf bank_mask:0xf
	v_mov_b32_dpp v47, v109 row_shl:1 row_mask:0xf bank_mask:0xf
	v_pk_fma_f32 v[30:31], v[108:109], v[62:63], v[30:31]
	v_pk_mul_f32 v[44:45], v[26:27], v[26:27]
	v_pk_fma_f32 v[30:31], v[58:59], v[46:47], v[30:31]
	v_pk_mul_f32 v[44:45], v[26:27], v[44:45]
	v_pk_mul_f32 v[46:47], v[30:31], v[30:31]
	v_pk_fma_f32 v[44:45], v[44:45], s[70:71], v[26:27] op_sel_hi:[1,0,1]
	v_pk_mul_f32 v[46:47], v[30:31], v[46:47]
	v_pk_mul_f32 v[44:45], v[44:45], s[72:73] op_sel_hi:[1,0]
	v_pk_fma_f32 v[46:47], v[46:47], s[70:71], v[30:31] op_sel_hi:[1,0,1]
	v_min_f32_e32 v44, 0x41e6d4ca, v44
	v_pk_mul_f32 v[46:47], v[46:47], s[72:73] op_sel_hi:[1,0]
	v_exp_f32_e32 v49, v44
	v_min_f32_e32 v44, 0x41e6d4ca, v45
	v_exp_f32_e32 v48, v44
	v_min_f32_e32 v44, 0x41e6d4ca, v46
	v_exp_f32_e32 v45, v44
	v_min_f32_e32 v44, 0x41e6d4ca, v47
	v_exp_f32_e32 v44, v44
	v_pk_add_f32 v[46:47], v[48:49], 1.0 op_sel_hi:[1,0]
	v_mov_b32_dpp v100, v36 row_shl:1 row_mask:0xf bank_mask:0xf
	v_pk_add_f32 v[44:45], v[44:45], 1.0 op_sel_hi:[1,0]
	v_mul_f32_e32 v48, v47, v46
	v_mul_f32_e32 v49, v45, v44
	v_mov_b32_dpp v101, v37 row_shl:1 row_mask:0xf bank_mask:0xf
	v_mul_f32_e32 v50, v48, v49
	v_rcp_f32_e32 v51, v50
	v_mov_b32_dpp v102, v38 row_shl:1 row_mask:0xf bank_mask:0xf
	v_mov_b32_dpp v103, v39 row_shl:1 row_mask:0xf bank_mask:0xf
	v_pk_mul_f32 v[4:5], v[4:5], v[194:195]
	v_mul_f32_e32 v50, v49, v51
	v_mul_f32_e32 v48, v48, v51
	v_pk_mul_f32 v[44:45], v[44:45], v[48:49] op_sel_hi:[1,0]
	v_pk_mul_f32 v[46:47], v[46:47], v[50:51] op_sel_hi:[1,0]
	v_pk_mul_f32 v[30:31], v[30:31], v[44:45]
	v_pk_mul_f32 v[26:27], v[26:27], v[46:47]
	v_pk_mul_f32 v[30:31], v[40:41], v[30:31]
	v_pk_mul_f32 v[40:41], v[42:43], v[26:27]
	v_cvt_pk_bf16_f32 v26, v24, v25
	v_mov_b64_e32 v[24:25], s[86:87]
	v_cvt_pk_bf16_f32 v27, v28, v29
	v_cvt_pk_bf16_f32 v29, v30, v31
	v_mad_i64_i32 v[30:31], s[10:11], v52, s90, v[24:25]
	v_cvt_pk_bf16_f32 v28, v40, v41
	v_lshl_add_u64 v[30:31], v[30:31], 0, v[112:113]
	global_store_dwordx4 v[30:31], v[26:29], off
	s_nop 0
	s_nop 0
	v_mov_b32_dpp v26, v116 row_ror:1 row_mask:0xf bank_mask:0xf
	v_mov_b32_dpp v27, v117 row_ror:1 row_mask:0xf bank_mask:0xf
	s_nop 0
	v_mov_b32_dpp v26, v22 row_shr:1 row_mask:0xf bank_mask:0xf
	v_mov_b32_dpp v27, v23 row_shr:1 row_mask:0xf bank_mask:0xf
	v_mov_b32_dpp v28, v114 row_ror:1 row_mask:0xf bank_mask:0xf
	v_mov_b32_dpp v29, v115 row_ror:1 row_mask:0xf bank_mask:0xf
	v_mov_b32_dpp v30, v36 row_ror:15 row_mask:0xf bank_mask:0xf
	v_mov_b32_dpp v31, v37 row_ror:15 row_mask:0xf bank_mask:0xf
	v_pk_fma_f32 v[26:27], v[80:81], v[26:27], v[84:85]
	v_mov_b32_dpp v28, v20 row_shr:1 row_mask:0xf bank_mask:0xf
	v_mov_b32_dpp v29, v21 row_shr:1 row_mask:0xf bank_mask:0xf
	v_mov_b32_dpp v30, v22 row_shl:1 row_mask:0xf bank_mask:0xf
	v_mov_b32_dpp v31, v23 row_shl:1 row_mask:0xf bank_mask:0xf
	v_pk_fma_f32 v[26:27], v[22:23], v[76:77], v[26:27]
	v_mov_b32_dpp v40, v38 row_ror:15 row_mask:0xf bank_mask:0xf
	v_mov_b32_dpp v41, v39 row_ror:15 row_mask:0xf bank_mask:0xf
	v_pk_fma_f32 v[28:29], v[82:83], v[28:29], v[86:87]
	v_pk_fma_f32 v[26:27], v[72:73], v[30:31], v[26:27]
	v_mov_b32_dpp v40, v20 row_shl:1 row_mask:0xf bank_mask:0xf
	v_mov_b32_dpp v41, v21 row_shl:1 row_mask:0xf bank_mask:0xf
	v_pk_fma_f32 v[28:29], v[20:21], v[78:79], v[28:29]
	v_pk_mul_f32 v[30:31], v[26:27], v[26:27]
	v_pk_fma_f32 v[28:29], v[74:75], v[40:41], v[28:29]
	v_pk_mul_f32 v[30:31], v[26:27], v[30:31]
	v_pk_mul_f32 v[40:41], v[28:29], v[28:29]
	v_pk_fma_f32 v[30:31], v[30:31], s[70:71], v[26:27] op_sel_hi:[1,0,1]
	v_pk_mul_f32 v[40:41], v[28:29], v[40:41]
	v_pk_mul_f32 v[30:31], v[30:31], s[72:73] op_sel_hi:[1,0]
	v_pk_fma_f32 v[40:41], v[40:41], s[70:71], v[28:29] op_sel_hi:[1,0,1]
	v_min_f32_e32 v30, 0x41e6d4ca, v30
	v_pk_mul_f32 v[40:41], v[40:41], s[72:73] op_sel_hi:[1,0]
	v_exp_f32_e32 v43, v30
	v_min_f32_e32 v30, 0x41e6d4ca, v31
	v_exp_f32_e32 v42, v30
	v_min_f32_e32 v30, 0x41e6d4ca, v40
	v_exp_f32_e32 v31, v30
	v_min_f32_e32 v30, 0x41e6d4ca, v41
	v_exp_f32_e32 v30, v30
	v_pk_add_f32 v[40:41], v[42:43], 1.0 op_sel_hi:[1,0]
	v_add_u32_e32 v46, 0xa0, v197
	v_pk_add_f32 v[30:31], v[30:31], 1.0 op_sel_hi:[1,0]
	v_mul_f32_e32 v42, v41, v40
	v_mul_f32_e32 v43, v31, v30
	v_mov_b32_dpp v96, v32 row_shl:1 row_mask:0xf bank_mask:0xf
	v_mul_f32_e32 v44, v42, v43
	v_rcp_f32_e32 v45, v44
	v_mov_b32_dpp v97, v33 row_shl:1 row_mask:0xf bank_mask:0xf
	v_mov_b32_dpp v98, v34 row_shl:1 row_mask:0xf bank_mask:0xf
	v_mov_b32_dpp v99, v35 row_shl:1 row_mask:0xf bank_mask:0xf
	v_mul_f32_e32 v44, v43, v45
	v_pk_mul_f32 v[40:41], v[40:41], v[44:45] op_sel_hi:[1,0]
	v_mul_f32_e32 v42, v42, v45
	v_pk_mul_f32 v[26:27], v[26:27], v[40:41]
	v_pk_mul_f32 v[30:31], v[30:31], v[42:43] op_sel_hi:[1,0]
	v_pk_mul_f32 v[12:13], v[12:13], v[26:27]
	v_pk_mul_f32 v[28:29], v[28:29], v[30:31]
	v_mov_b32_dpp v26, v110 row_ror:1 row_mask:0xf bank_mask:0xf
	v_mov_b32_dpp v27, v111 row_ror:1 row_mask:0xf bank_mask:0xf
	v_pk_mul_f32 v[14:15], v[14:15], v[28:29]
	v_mov_b32_dpp v26, v18 row_shr:1 row_mask:0xf bank_mask:0xf
	v_mov_b32_dpp v27, v19 row_shr:1 row_mask:0xf bank_mask:0xf
	v_mov_b32_dpp v28, v108 row_ror:1 row_mask:0xf bank_mask:0xf
	v_mov_b32_dpp v29, v109 row_ror:1 row_mask:0xf bank_mask:0xf
	v_mov_b32_dpp v30, v32 row_ror:15 row_mask:0xf bank_mask:0xf
	v_mov_b32_dpp v31, v33 row_ror:15 row_mask:0xf bank_mask:0xf
	v_pk_fma_f32 v[26:27], v[64:65], v[26:27], v[68:69]
	v_mov_b32_dpp v28, v16 row_shr:1 row_mask:0xf bank_mask:0xf
	v_mov_b32_dpp v29, v17 row_shr:1 row_mask:0xf bank_mask:0xf
	v_mov_b32_dpp v30, v18 row_shl:1 row_mask:0xf bank_mask:0xf
	v_mov_b32_dpp v31, v19 row_shl:1 row_mask:0xf bank_mask:0xf
	v_pk_fma_f32 v[26:27], v[18:19], v[60:61], v[26:27]
	v_mov_b32_dpp v40, v34 row_ror:15 row_mask:0xf bank_mask:0xf
	v_mov_b32_dpp v41, v35 row_ror:15 row_mask:0xf bank_mask:0xf
	v_pk_fma_f32 v[28:29], v[66:67], v[28:29], v[70:71]
	v_pk_fma_f32 v[26:27], v[56:57], v[30:31], v[26:27]
	v_mov_b32_dpp v40, v16 row_shl:1 row_mask:0xf bank_mask:0xf
	v_mov_b32_dpp v41, v17 row_shl:1 row_mask:0xf bank_mask:0xf
	v_pk_fma_f32 v[28:29], v[16:17], v[62:63], v[28:29]
	v_pk_mul_f32 v[30:31], v[26:27], v[26:27]
	v_pk_fma_f32 v[28:29], v[58:59], v[40:41], v[28:29]
	v_pk_mul_f32 v[30:31], v[26:27], v[30:31]
	v_pk_mul_f32 v[40:41], v[28:29], v[28:29]
	v_pk_fma_f32 v[30:31], v[30:31], s[70:71], v[26:27] op_sel_hi:[1,0,1]
	v_pk_mul_f32 v[40:41], v[28:29], v[40:41]
	v_pk_mul_f32 v[30:31], v[30:31], s[72:73] op_sel_hi:[1,0]
	v_pk_fma_f32 v[40:41], v[40:41], s[70:71], v[28:29] op_sel_hi:[1,0,1]
	v_min_f32_e32 v30, 0x41e6d4ca, v30
	v_pk_mul_f32 v[40:41], v[40:41], s[72:73] op_sel_hi:[1,0]
	v_exp_f32_e32 v43, v30
	v_min_f32_e32 v30, 0x41e6d4ca, v31
	v_exp_f32_e32 v42, v30
	v_min_f32_e32 v30, 0x41e6d4ca, v40
	v_exp_f32_e32 v31, v30
	v_min_f32_e32 v30, 0x41e6d4ca, v41
	v_exp_f32_e32 v30, v30
	v_pk_add_f32 v[40:41], v[42:43], 1.0 op_sel_hi:[1,0]
	v_pk_mul_f32 v[0:1], v[0:1], v[194:195]
	v_pk_add_f32 v[30:31], v[30:31], 1.0 op_sel_hi:[1,0]
	v_mul_f32_e32 v42, v41, v40
	v_mul_f32_e32 v43, v31, v30
	s_nop 0
	v_mul_f32_e32 v44, v42, v43
	v_rcp_f32_e32 v45, v44
	s_nop 0
	v_mul_f32_e32 v44, v43, v45
	v_mul_f32_e32 v42, v42, v45
	v_pk_mul_f32 v[30:31], v[30:31], v[42:43] op_sel_hi:[1,0]
	v_pk_mul_f32 v[40:41], v[40:41], v[44:45] op_sel_hi:[1,0]
	v_pk_mul_f32 v[28:29], v[28:29], v[30:31]
	v_pk_mul_f32 v[26:27], v[26:27], v[40:41]
	v_pk_mul_f32 v[28:29], v[10:11], v[28:29]
	v_pk_mul_f32 v[10:11], v[8:9], v[26:27]
	v_cvt_pk_bf16_f32 v8, v12, v13
	v_mad_i64_i32 v[12:13], s[10:11], v46, s90, v[24:25]
	v_cvt_pk_bf16_f32 v9, v14, v15
	v_cvt_pk_bf16_f32 v10, v10, v11
	v_cvt_pk_bf16_f32 v11, v28, v29
	v_lshl_add_u64 v[12:13], v[12:13], 0, v[112:113]
	global_store_dwordx4 v[12:13], v[8:11], off
	v_add_u32_e32 v30, 0xb0, v197
	s_nop 0
	v_mov_b32_dpp v8, v22 row_ror:1 row_mask:0xf bank_mask:0xf
	v_mov_b32_dpp v9, v23 row_ror:1 row_mask:0xf bank_mask:0xf
	s_nop 0
	v_mov_b32_dpp v8, v36 row_shr:1 row_mask:0xf bank_mask:0xf
	v_mov_b32_dpp v9, v37 row_shr:1 row_mask:0xf bank_mask:0xf
	v_mov_b32_dpp v10, v20 row_ror:1 row_mask:0xf bank_mask:0xf
	v_mov_b32_dpp v11, v21 row_ror:1 row_mask:0xf bank_mask:0xf
	v_pk_fma_f32 v[8:9], v[80:81], v[8:9], v[84:85]
	v_mov_b32_dpp v10, v38 row_shr:1 row_mask:0xf bank_mask:0xf
	v_mov_b32_dpp v11, v39 row_shr:1 row_mask:0xf bank_mask:0xf
	v_pk_fma_f32 v[8:9], v[36:37], v[76:77], v[8:9]
	v_pk_fma_f32 v[10:11], v[82:83], v[10:11], v[86:87]
	v_pk_fma_f32 v[8:9], v[72:73], v[100:101], v[8:9]
	v_pk_fma_f32 v[10:11], v[38:39], v[78:79], v[10:11]
	v_pk_mul_f32 v[12:13], v[8:9], v[8:9]
	v_pk_fma_f32 v[10:11], v[74:75], v[102:103], v[10:11]
	v_pk_mul_f32 v[12:13], v[8:9], v[12:13]
	v_pk_mul_f32 v[14:15], v[10:11], v[10:11]
	v_pk_fma_f32 v[12:13], v[12:13], s[70:71], v[8:9] op_sel_hi:[1,0,1]
	v_pk_mul_f32 v[14:15], v[10:11], v[14:15]
	v_pk_mul_f32 v[12:13], v[12:13], s[72:73] op_sel_hi:[1,0]
	v_pk_fma_f32 v[14:15], v[14:15], s[70:71], v[10:11] op_sel_hi:[1,0,1]
	v_min_f32_e32 v12, 0x41e6d4ca, v12
	v_pk_mul_f32 v[14:15], v[14:15], s[72:73] op_sel_hi:[1,0]
	v_exp_f32_e32 v21, v12
	v_min_f32_e32 v12, 0x41e6d4ca, v13
	v_exp_f32_e32 v20, v12
	v_min_f32_e32 v12, 0x41e6d4ca, v14
	v_exp_f32_e32 v13, v12
	v_min_f32_e32 v12, 0x41e6d4ca, v15
	v_exp_f32_e32 v12, v12
	v_pk_add_f32 v[14:15], v[20:21], 1.0 op_sel_hi:[1,0]
	v_pk_add_f32 v[12:13], v[12:13], 1.0 op_sel_hi:[1,0]
	v_mul_f32_e32 v20, v15, v14
	v_mul_f32_e32 v21, v13, v12
	s_nop 0
	v_mul_f32_e32 v22, v20, v21
	v_rcp_f32_e32 v23, v22
	s_nop 0
	v_mul_f32_e32 v20, v20, v23
	v_pk_mul_f32 v[12:13], v[12:13], v[20:21] op_sel_hi:[1,0]
	v_mul_f32_e32 v22, v21, v23
	v_pk_mul_f32 v[12:13], v[10:11], v[12:13]
	v_pk_mul_f32 v[14:15], v[14:15], v[22:23] op_sel_hi:[1,0]
	v_pk_mul_f32 v[20:21], v[6:7], v[12:13]
	v_pk_mul_f32 v[14:15], v[8:9], v[14:15]
	v_mov_b32_dpp v12, v18 row_ror:1 row_mask:0xf bank_mask:0xf
	v_mov_b32_dpp v13, v19 row_ror:1 row_mask:0xf bank_mask:0xf
	v_pk_mul_f32 v[22:23], v[4:5], v[14:15]
	v_mov_b32_dpp v12, v32 row_shr:1 row_mask:0xf bank_mask:0xf
	v_mov_b32_dpp v13, v33 row_shr:1 row_mask:0xf bank_mask:0xf
	v_mov_b32_dpp v14, v16 row_ror:1 row_mask:0xf bank_mask:0xf
	v_mov_b32_dpp v15, v17 row_ror:1 row_mask:0xf bank_mask:0xf
	v_pk_fma_f32 v[12:13], v[64:65], v[12:13], v[68:69]
	v_mov_b32_dpp v14, v34 row_shr:1 row_mask:0xf bank_mask:0xf
	v_mov_b32_dpp v15, v35 row_shr:1 row_mask:0xf bank_mask:0xf
	v_pk_fma_f32 v[12:13], v[32:33], v[60:61], v[12:13]
	v_pk_fma_f32 v[14:15], v[66:67], v[14:15], v[70:71]
	v_pk_fma_f32 v[12:13], v[56:57], v[96:97], v[12:13]
	v_pk_fma_f32 v[14:15], v[34:35], v[62:63], v[14:15]
	v_pk_mul_f32 v[16:17], v[12:13], v[12:13]
	v_pk_fma_f32 v[14:15], v[58:59], v[98:99], v[14:15]
	v_pk_mul_f32 v[16:17], v[12:13], v[16:17]
	v_pk_mul_f32 v[18:19], v[14:15], v[14:15]
	v_pk_fma_f32 v[16:17], v[16:17], s[70:71], v[12:13] op_sel_hi:[1,0,1]
	v_pk_mul_f32 v[18:19], v[14:15], v[18:19]
	v_pk_mul_f32 v[16:17], v[16:17], s[72:73] op_sel_hi:[1,0]
	v_pk_fma_f32 v[18:19], v[18:19], s[70:71], v[14:15] op_sel_hi:[1,0,1]
	v_min_f32_e32 v16, 0x41e6d4ca, v16
	v_pk_mul_f32 v[18:19], v[18:19], s[72:73] op_sel_hi:[1,0]
	v_exp_f32_e32 v27, v16
	v_min_f32_e32 v16, 0x41e6d4ca, v17
	v_exp_f32_e32 v26, v16
	v_min_f32_e32 v16, 0x41e6d4ca, v18
	v_exp_f32_e32 v17, v16
	v_min_f32_e32 v16, 0x41e6d4ca, v19
	v_exp_f32_e32 v16, v16
	v_pk_add_f32 v[18:19], v[26:27], 1.0 op_sel_hi:[1,0]
	v_pk_add_f32 v[16:17], v[16:17], 1.0 op_sel_hi:[1,0]
	v_mul_f32_e32 v26, v19, v18
	v_mul_f32_e32 v27, v17, v16
	s_nop 0
	v_mul_f32_e32 v28, v26, v27
	v_rcp_f32_e32 v29, v28
	s_nop 0
	v_mul_f32_e32 v28, v27, v29
	v_mul_f32_e32 v26, v26, v29
	v_pk_mul_f32 v[16:17], v[16:17], v[26:27] op_sel_hi:[1,0]
	v_pk_mul_f32 v[18:19], v[18:19], v[28:29] op_sel_hi:[1,0]
	v_pk_mul_f32 v[16:17], v[14:15], v[16:17]
	v_pk_mul_f32 v[18:19], v[12:13], v[18:19]
	v_pk_mul_f32 v[26:27], v[2:3], v[16:17]
	v_pk_mul_f32 v[18:19], v[0:1], v[18:19]
	v_cvt_pk_bf16_f32 v17, v20, v21
	v_mad_i64_i32 v[20:21], s[10:11], v30, s90, v[24:25]
	v_cvt_pk_bf16_f32 v16, v22, v23
	v_cvt_pk_bf16_f32 v18, v18, v19
	v_cvt_pk_bf16_f32 v19, v26, v27
	v_lshl_add_u64 v[20:21], v[20:21], 0, v[112:113]
	global_store_dwordx4 v[20:21], v[16:19], off
	s_and_saveexec_b64 s[10:11], s[64:65]
	s_cbranch_execz .LBB0_784
	s_add_u32 s14, s4, s14
	s_addc_u32 s15, s5, s12
	v_lshl_add_u64 v[16:17], v[192:193], 2, s[14:15]
	global_store_dwordx4 v[16:17], v[8:11], off
	s_nop 1
	v_add_co_u32_e32 v8, vcc, 0x2000, v16
	s_nop 1
	v_addc_co_u32_e32 v9, vcc, 0, v17, vcc
	v_add_co_u32_e32 v10, vcc, 0x5000, v16
	global_store_dwordx4 v[8:9], v[36:39], off offset:3072
	s_nop 0
	v_addc_co_u32_e32 v11, vcc, 0, v17, vcc
	global_store_dwordx4 v[10:11], v[4:7], off offset:2048
	global_store_dwordx4 v[16:17], v[12:15], off offset:16
	global_store_dwordx4 v[8:9], v[32:35], off offset:3088
	global_store_dwordx4 v[10:11], v[0:3], off offset:2064
